# attention unit epilogue: row-sum butterflies via DPP and v_permlane16_swap instead of 80 ds_bpermute round trips (strategy 7: intra-wave movement via DPP)
# speedup vs baseline: 1.0097x; 1.0097x over previous
; #define SBAR() __builtin_amdgcn_sched_barrier(0)
; #define BAR() do { asm volatile("s_waitcnt lgkmcnt(0)" ::: "memory"); __builtin_amdgcn_s_barrier(); asm volatile("" ::: "memory"); } while (0)
; #define RESC(a) do { if (__any((a) < 1.f)) { if (hi == 0) al_l[r32] = (a); asm volatile("s_waitcnt lgkmcnt(0)" ::: "memory"); \
;     _Pragma("unroll") for (int d = 0; d < 4; ++d) _Pragma("unroll") for (int r = 0; r < 16; ++r) o[d][r] *= al_l[crow(r, hi)]; } } while (0)
; __device__ __forceinline__ void partialSM(f32x16& p0, f32x16& p1, float& M, float& alpha) {
;   float pmax = p0[0];
; #pragma unroll
;   for (int r = 1; r < 16; ++r) pmax = fmaxf(pmax, p0[r]);
; #pragma unroll
;   for (int r = 0; r < 16; ++r) pmax = fmaxf(pmax, p1[r]);
;   { auto rr = __builtin_amdgcn_permlane32_swap(__float_as_uint(pmax), __float_as_uint(pmax), false, false);
;     pmax = fmaxf(__uint_as_float(rr[0]), __uint_as_float(rr[1])); }
;   const float mn = fmaxf(M, pmax);
;   alpha = __builtin_amdgcn_exp2f(M - mn); M = mn;
; #pragma unroll
;   for (int r = 0; r < 16; ++r) { p0[r] -= mn; p1[r] -= mn; }
; #pragma unroll
;   for (int r = 0; r < 16; ++r) p0[r] = __builtin_amdgcn_exp2f(p0[r]);
; }
; __device__ __forceinline__ void finishSM(f32x16& p0, f32x16& p1, float alpha, float& l_reg, bf16x8& pa0, bf16x8& pa1, bf16x8& pa2, bf16x8& pa3) {
; #pragma unroll
;   for (int r = 0; r < 16; ++r) p1[r] = __builtin_amdgcn_exp2f(p1[r]);
;   float ps = 0;
; #pragma unroll
;   for (int r = 0; r < 16; ++r) ps += p0[r];
; #pragma unroll
;   for (int r = 0; r < 16; ++r) ps += p1[r];
;   { auto rr = __builtin_amdgcn_permlane32_swap(__float_as_uint(ps), __float_as_uint(ps), false, false);
;     ps = __uint_as_float(rr[0]) + __uint_as_float(rr[1]); }
;   l_reg = l_reg * alpha + ps;
;     ...
;   PK4(p0, 0, pa0); PK4(p0, 8, pa1); PK4(p1, 0, pa2); PK4(p1, 8, pa3);
;     ...
; }
; __device__ __forceinline__ void attn_body(const bf16_t* __restrict__ Qb, const bf16_t* __restrict__ KVb, int hcol, bf16_t* __restrict__ Ob, float* __restrict__ rsqa, int seq, char* lds) {
;     ...
;   pv_d0(o, vb0, pa0, pa1, pa2, pa3); partialSM(pB0, pB1, m_reg, alB);
;   SBAR(); asm volatile("s_waitcnt vmcnt(0)" ::: "memory"); RESC(alB); BAR();
;   finishSM(pB0, pB1, alB, l_reg, pa0, pa1, pa2, pa3);
;   pv_d0(o, vb0 + SHM_V, pa0, pa1, pa2, pa3);
.LBB0_674:
	v_sub_f32_e32 v68, v96, v67
	v_sub_f32_e32 v70, v97, v67
	v_sub_f32_e32 v72, v98, v67
	v_sub_f32_e32 v74, v99, v67
	v_sub_f32_e32 v76, v100, v67
	v_sub_f32_e32 v78, v101, v67
	v_sub_f32_e32 v80, v102, v67
	v_sub_f32_e32 v82, v103, v67
	v_exp_f32_e32 v138, v68
	v_exp_f32_e32 v139, v70
	v_exp_f32_e32 v140, v72
	v_exp_f32_e32 v141, v74
	v_exp_f32_e32 v142, v76
	v_exp_f32_e32 v143, v78
	v_exp_f32_e32 v144, v80
	v_exp_f32_e32 v145, v82
	v_sub_f32_e32 v69, v112, v67
	v_sub_f32_e32 v71, v113, v67
	v_exp_f32_e32 v154, v69
	v_exp_f32_e32 v155, v71
	v_cvt_pk_bf16_f32 v68, v138, v139
	v_cvt_pk_bf16_f32 v69, v140, v141
	v_cvt_pk_bf16_f32 v70, v142, v143
	v_cvt_pk_bf16_f32 v71, v144, v145
	s_nop 0
	v_permlane32_swap_b32_e32 v68, v70
	v_permlane32_swap_b32_e32 v69, v71
	v_sub_f32_e32 v84, v104, v67
	v_sub_f32_e32 v85, v120, v67
	v_sub_f32_e32 v86, v105, v67
	v_sub_f32_e32 v87, v121, v67
	v_sub_f32_e32 v88, v106, v67
	v_sub_f32_e32 v89, v122, v67
	v_sub_f32_e32 v90, v107, v67
	v_sub_f32_e32 v91, v123, v67
	v_sub_f32_e32 v92, v108, v67
	v_sub_f32_e32 v93, v124, v67
	v_sub_f32_e32 v94, v109, v67
	v_sub_f32_e32 v95, v125, v67
	v_sub_f32_e32 v96, v110, v67
	v_sub_f32_e32 v97, v126, v67
	v_sub_f32_e32 v98, v111, v67
	s_waitcnt lgkmcnt(0)
	s_barrier
	v_exp_f32_e32 v146, v84
	v_exp_f32_e32 v147, v86
	v_exp_f32_e32 v148, v88
	v_exp_f32_e32 v149, v90
	v_exp_f32_e32 v150, v92
	v_exp_f32_e32 v151, v94
	v_exp_f32_e32 v152, v96
	v_exp_f32_e32 v153, v98
	v_exp_f32_e32 v193, v85
	v_exp_f32_e32 v194, v87
	v_exp_f32_e32 v195, v89
	v_exp_f32_e32 v196, v91
	v_exp_f32_e32 v197, v93
	v_exp_f32_e32 v198, v95
	v_exp_f32_e32 v199, v97
	ds_read_b64_tr_b16 v[86:87], v188 offset:18432
	ds_read_b64_tr_b16 v[88:89], v188 offset:22528
	ds_read_b64_tr_b16 v[90:91], v188 offset:26624
	ds_read_b64_tr_b16 v[92:93], v188 offset:30720
	ds_read_b64_tr_b16 v[84:85], v188 offset:16384
	ds_read_b64_tr_b16 v[94:95], v188 offset:16896
	ds_read_b64_tr_b16 v[98:99], v188 offset:17408
	ds_read_b64_tr_b16 v[102:103], v188 offset:17920
	ds_read_b64_tr_b16 v[96:97], v188 offset:18944
	ds_read_b64_tr_b16 v[100:101], v188 offset:19456
	ds_read_b64_tr_b16 v[104:105], v188 offset:19968
	s_waitcnt lgkmcnt(2)
	v_mfma_f32_32x32x16_bf16 v[48:63], v[68:71], v[94:97], v[48:63]
	v_sub_f32_e32 v73, v114, v67
	v_sub_f32_e32 v75, v115, v67
	v_exp_f32_e32 v156, v73
	v_exp_f32_e32 v157, v75
	v_cvt_pk_bf16_f32 v72, v146, v147
	v_cvt_pk_bf16_f32 v73, v148, v149
	v_cvt_pk_bf16_f32 v74, v150, v151
	v_cvt_pk_bf16_f32 v75, v152, v153
	s_nop 0
	v_permlane32_swap_b32_e32 v72, v74
	v_permlane32_swap_b32_e32 v73, v75
	v_sub_f32_e32 v77, v116, v67
	v_sub_f32_e32 v79, v117, v67
	v_sub_f32_e32 v81, v118, v67
	v_sub_f32_e32 v83, v119, v67
	v_mfma_f32_32x32x16_bf16 v[0:15], v[68:71], v[84:87], v[0:15]
	ds_read_b64_tr_b16 v[86:87], v188 offset:20480
	ds_read_b64_tr_b16 v[106:107], v188 offset:20992
	ds_read_b64_tr_b16 v[110:111], v188 offset:21504
	ds_read_b64_tr_b16 v[114:115], v188 offset:22016
	ds_read_b64_tr_b16 v[108:109], v188 offset:23040
	ds_read_b64_tr_b16 v[112:113], v188 offset:23552
	ds_read_b64_tr_b16 v[116:117], v188 offset:24064
	v_exp_f32_e32 v158, v77
	v_exp_f32_e32 v159, v79
	v_exp_f32_e32 v191, v81
	v_exp_f32_e32 v192, v83
	v_cvt_pk_bf16_f32 v76, v154, v155
	v_cvt_pk_bf16_f32 v77, v156, v157
	s_waitcnt lgkmcnt(2)
	v_mfma_f32_32x32x16_bf16 v[48:63], v[72:75], v[106:109], v[48:63]
	v_cvt_pk_bf16_f32 v78, v158, v159
	v_cvt_pk_bf16_f32 v79, v191, v192
	s_nop 0
	v_permlane32_swap_b32_e32 v76, v78
	v_permlane32_swap_b32_e32 v77, v79
	v_sub_f32_e32 v67, v127, v67
	v_mfma_f32_32x32x16_bf16 v[0:15], v[72:75], v[86:89], v[0:15]
	ds_read_b64_tr_b16 v[88:89], v188 offset:24576
	ds_read_b64_tr_b16 v[84:85], v188 offset:25088
	ds_read_b64_tr_b16 v[118:119], v188 offset:25600
	ds_read_b64_tr_b16 v[122:123], v188 offset:26112
	ds_read_b64_tr_b16 v[86:87], v188 offset:27136
	ds_read_b64_tr_b16 v[120:121], v188 offset:27648
	ds_read_b64_tr_b16 v[124:125], v188 offset:28160
	v_exp_f32_e32 v67, v67
	v_cvt_pk_bf16_f32 v80, v193, v194
	v_cvt_pk_bf16_f32 v81, v195, v196
	v_cvt_pk_bf16_f32 v82, v197, v198
	v_cvt_pk_bf16_f32 v83, v199, v67
	s_nop 0
	v_permlane32_swap_b32_e32 v80, v82
	s_waitcnt lgkmcnt(2)
	v_mfma_f32_32x32x16_bf16 v[48:63], v[76:79], v[84:87], v[48:63]
	v_add_f32_e32 v84, 0, v138
	v_add_f32_e32 v84, v139, v84
	v_add_f32_e32 v84, v140, v84
	v_add_f32_e32 v84, v141, v84
	v_add_f32_e32 v84, v142, v84
	v_add_f32_e32 v84, v143, v84
	v_add_f32_e32 v84, v144, v84
	v_mfma_f32_32x32x16_bf16 v[32:47], v[68:71], v[98:101], v[32:47]
	v_add_f32_e32 v84, v145, v84
	v_add_f32_e32 v84, v146, v84
	v_add_f32_e32 v84, v147, v84
	v_add_f32_e32 v84, v148, v84
	v_add_f32_e32 v84, v149, v84
	v_add_f32_e32 v84, v150, v84
	v_add_f32_e32 v84, v151, v84
	v_mfma_f32_32x32x16_bf16 v[16:31], v[68:71], v[102:105], v[16:31]
	v_add_f32_e32 v68, v152, v84
	v_add_f32_e32 v68, v153, v68
	v_add_f32_e32 v68, v154, v68
	v_add_f32_e32 v68, v155, v68
	v_add_f32_e32 v68, v156, v68
	v_add_f32_e32 v68, v157, v68
	v_add_f32_e32 v68, v158, v68
	v_mfma_f32_32x32x16_bf16 v[32:47], v[72:75], v[110:113], v[32:47]
	v_permlane32_swap_b32_e32 v81, v83
	v_add_f32_e32 v68, v159, v68
	v_add_f32_e32 v68, v191, v68
	v_add_f32_e32 v68, v192, v68
	v_add_f32_e32 v68, v193, v68
	v_add_f32_e32 v68, v194, v68
	v_mfma_f32_32x32x16_bf16 v[16:31], v[72:75], v[114:117], v[16:31]
	v_add_f32_e32 v68, v195, v68
	v_add_f32_e32 v68, v196, v68
	v_add_f32_e32 v68, v197, v68
	v_add_f32_e32 v68, v198, v68
	v_add_f32_e32 v68, v199, v68
	v_add_f32_e32 v67, v67, v68
	v_mov_b32_e32 v68, v67
	v_mfma_f32_32x32x16_bf16 v[0:15], v[76:79], v[88:91], v[0:15]
	ds_read_b64_tr_b16 v[90:91], v188 offset:28672
	ds_read_b64_tr_b16 v[126:127], v188 offset:29184
	ds_read_b64_tr_b16 v[130:131], v188 offset:29696
	ds_read_b64_tr_b16 v[134:135], v188 offset:30208
	ds_read_b64_tr_b16 v[128:129], v188 offset:31232
	ds_read_b64_tr_b16 v[132:133], v188 offset:31744
	ds_read_b64_tr_b16 v[136:137], v188 offset:32256
	v_permlane32_swap_b32_e32 v67, v68
	s_waitcnt lgkmcnt(8)
; __device__ __forceinline__ int crow(int r, int hi) { return (r & 3) + 8 * (r >> 2) + 4 * hi; }
; __device__ __forceinline__ unsigned cvtpk(float lo, float hi) { const f32x2_t v = {lo, hi}; return __builtin_bit_cast(unsigned, __builtin_convertvector(v, bf16x2_t)); }
; __device__ __forceinline__ void attn_body(const bf16_t* __restrict__ Qb, const bf16_t* __restrict__ KVb, int hcol, bf16_t* __restrict__ Ob, float* __restrict__ rsqa, int seq, char* lds) {
;     ...
;   pv_d0(o, vb0 + SHM_V, pa0, pa1, pa2, pa3);
;   if (hi == 0) li_l[r32] = l_reg; asm volatile("s_waitcnt lgkmcnt(0)" ::: "memory");
;   float rli[16];
; #pragma unroll
;   for (int r = 0; r < 16; ++r) rli[r] = __builtin_amdgcn_rcpf(li_l[crow(r, hi)]);
;   bf16_t* Ow = Ob + (long)(wid * QBLK) * LDO;
; #pragma unroll
;   for (int r = 0; r < 16; ++r) { int orow = crow(r, hi); float sq = 0.f;
; #pragma unroll
;     for (int d0 = 0; d0 < 4; ++d0) { const float v = o[d0][r] * rli[r]; sq += v * v; Ow[(long)orow * LDO + d0 * 32 + r32] = (bf16_t)(cvtpk(v, 0.f) & 0xffffu); }
;     sq += __shfl_xor(sq, 1); sq += __shfl_xor(sq, 2); sq += __shfl_xor(sq, 4); sq += __shfl_xor(sq, 8); sq += __shfl_xor(sq, 16);
;     if (r32 == 0) atomicAdd(rsqa + wid * QBLK + orow, sq); }
	v_mfma_f32_32x32x16_bf16 v[32:47], v[76:79], v[118:121], v[32:47]
	s_waitcnt lgkmcnt(7)
	v_mfma_f32_32x32x16_bf16 v[16:31], v[76:79], v[122:125], v[16:31]
	s_waitcnt lgkmcnt(6)
	v_mfma_f32_32x32x16_bf16 v[0:15], v[80:83], v[90:93], v[0:15]
	s_waitcnt lgkmcnt(2)
	v_mfma_f32_32x32x16_bf16 v[48:63], v[80:83], v[126:129], v[48:63]
	s_waitcnt lgkmcnt(1)
	v_mfma_f32_32x32x16_bf16 v[32:47], v[80:83], v[130:133], v[32:47]
	s_waitcnt lgkmcnt(0)
	v_mfma_f32_32x32x16_bf16 v[16:31], v[80:83], v[134:137], v[16:31]
	s_and_saveexec_b64 s[10:11], s[4:5]
	v_add_f32_e32 v64, v64, v65
	v_fmac_f32_e32 v64, v190, v205
	v_add_f32_e32 v65, v67, v68
	v_fmac_f32_e32 v65, v64, v66
	ds_write_b32 v189, v65
	s_or_b64 exec, exec, s[10:11]
	s_waitcnt lgkmcnt(0)
	v_add_u32_e32 v64, s1, v166
	ds_read_b128 v[76:79], v64
	ds_read_b128 v[72:75], v64 offset:32
	v_and_b32_e32 v84, 64, v170
	v_xor_b32_e32 v83, 1, v170
	v_add_u32_e32 v145, 64, v84
	s_waitcnt lgkmcnt(1)
	v_rcp_f32_e32 v82, v76
	v_cmp_lt_i32_e32 vcc, v83, v145
	s_ashr_i32 s37, s36, 31
	s_lshl_b64 s[4:5], s[6:7], 2
	v_mul_f32_e32 v48, v48, v82
	v_cndmask_b32_e32 v83, v170, v83, vcc
	v_mul_f32_e32 v0, v0, v82
	v_mul_f32_e32 v84, v48, v48
	v_lshlrev_b32_e32 v140, 2, v83
	v_xor_b32_e32 v83, 2, v170
	v_fmac_f32_e32 v84, v0, v0
	v_mul_f32_e32 v32, v32, v82
	v_cmp_lt_i32_e32 vcc, v83, v145
	v_fmac_f32_e32 v84, v32, v32
	v_mul_f32_e32 v85, v16, v82
	v_cndmask_b32_e32 v83, v170, v83, vcc
	v_fmac_f32_e32 v84, v85, v85
	v_lshlrev_b32_e32 v141, 2, v83
	v_xor_b32_e32 v83, 4, v170
	s_nop 1
	v_mov_b32_dpp v16, v84 quad_perm:[1,0,3,2] row_mask:0xf bank_mask:0xf
	v_cmp_lt_i32_e32 vcc, v83, v145
	s_add_u32 s6, s14, s4
	s_addc_u32 s7, s15, s5
	v_cndmask_b32_e32 v83, v170, v83, vcc
	v_lshlrev_b32_e32 v142, 2, v83
	v_xor_b32_e32 v83, 8, v170
	v_cmp_lt_i32_e32 vcc, v83, v145
	s_waitcnt lgkmcnt(0)
	v_add_f32_e32 v16, v84, v16
	s_lshl_b64 s[4:5], s[36:37], 2
	v_cndmask_b32_e32 v83, v170, v83, vcc
	v_lshlrev_b32_e32 v143, 2, v83
	s_nop 1
	v_mov_b32_dpp v83, v16 quad_perm:[2,3,0,1] row_mask:0xf bank_mask:0xf
	s_add_u32 s6, s6, s4
	s_addc_u32 s7, s7, s5
	s_lshl_b64 s[4:5], s[8:9], 12
	s_add_u32 s8, s33, s4
	s_waitcnt lgkmcnt(0)
	v_add_f32_e32 v16, v16, v83
	s_nop 1
	v_mov_b32_dpp v84, v16 row_half_mirror row_mask:0xf bank_mask:0xf
	s_addc_u32 s9, s34, s5
	s_ashr_i32 s1, s0, 31
	s_lshl_b64 s[4:5], s[0:1], 12
	s_add_u32 s4, s8, s4
	s_waitcnt lgkmcnt(0)
	v_add_f32_e32 v16, v16, v84
	s_nop 1
	v_mov_b32_dpp v84, v16 row_mirror row_mask:0xf bank_mask:0xf
	v_xor_b32_e32 v82, 16, v170
	s_addc_u32 s5, s9, s5
	v_lshlrev_b32_e32 v166, 1, v187
	v_cmp_lt_i32_e32 vcc, v82, v145
	s_lshl_b64 s[0:1], s[0:1], 2
	v_lshl_add_u64 v[80:81], s[4:5], 0, v[166:167]
	v_cndmask_b32_e32 v82, v170, v82, vcc
	s_add_u32 s0, s6, s0
	v_lshlrev_b32_e32 v166, 14, v186
	v_lshlrev_b32_e32 v144, 2, v82
	v_lshl_add_u64 v[82:83], v[80:81], 0, v[166:167]
	v_cvt_pk_bf16_f32 v0, v0, s0
	ds_read_b128 v[68:71], v64 offset:64
	ds_read_b128 v[64:67], v64 offset:96
	global_store_short v[82:83], v0, off
	v_cvt_pk_bf16_f32 v0, v48, s0
	s_waitcnt lgkmcnt(0)
	v_add_f32_e32 v16, v16, v84
	global_store_short v[82:83], v0, off offset:64
	v_cvt_pk_bf16_f32 v0, v32, s0
	v_mov_b32_e32 v244, v16
	v_mov_b32_e32 v32, v16
	s_nop 1
	v_permlane16_swap_b32_e32 v244, v32
	v_lshlrev_b32_e32 v76, 2, v186
	global_store_short v[82:83], v0, off offset:128
	v_cvt_pk_bf16_f32 v0, v85, s0
	v_cmp_eq_u32_e32 vcc, 0, v187
	s_addc_u32 s1, s7, s1
	global_store_short v[82:83], v0, off offset:192
	v_lshlrev_b32_e32 v0, 2, v76
	s_and_saveexec_b64 s[4:5], vcc
	s_cbranch_execz .LBB0_678
	s_waitcnt lgkmcnt(0)
	v_add_f32_e32 v16, v16, v32
	global_atomic_add_f32 v0, v16, s[0:1]
.LBB0_678:
	s_or_b64 exec, exec, s[4:5]
	v_rcp_f32_e32 v16, v77
	v_lshl_or_b32 v166, v76, 12, v171
	v_mul_f32_e32 v48, v49, v16
	v_mul_f32_e32 v1, v1, v16
	s_waitcnt lgkmcnt(0)
	v_mul_f32_e32 v32, v48, v48
	v_mul_f32_e32 v49, v33, v16
	v_fmac_f32_e32 v32, v1, v1
	v_fmac_f32_e32 v32, v49, v49
	v_mul_f32_e32 v17, v17, v16
	v_fmac_f32_e32 v32, v17, v17
	s_nop 1
	v_mov_b32_dpp v16, v32 quad_perm:[1,0,3,2] row_mask:0xf bank_mask:0xf
	v_cvt_pk_bf16_f32 v1, v1, s0
	v_cvt_pk_bf16_f32 v17, v17, s0
	s_waitcnt lgkmcnt(0)
	v_add_f32_e32 v16, v32, v16
	s_nop 1
	v_mov_b32_dpp v32, v16 quad_perm:[2,3,0,1] row_mask:0xf bank_mask:0xf
	s_waitcnt lgkmcnt(0)
	v_add_f32_e32 v16, v16, v32
	s_nop 1
	v_mov_b32_dpp v77, v16 row_half_mirror row_mask:0xf bank_mask:0xf
	v_lshl_add_u64 v[32:33], v[80:81], 0, v[166:167]
	global_store_short v[32:33], v1, off
	v_cvt_pk_bf16_f32 v1, v48, s0
	global_store_short v[32:33], v1, off offset:64
	s_waitcnt lgkmcnt(0)
	v_add_f32_e32 v16, v16, v77
	s_nop 1
	v_mov_b32_dpp v77, v16 row_mirror row_mask:0xf bank_mask:0xf
	v_cvt_pk_bf16_f32 v48, v49, s0
	global_store_short v[32:33], v48, off offset:128
	global_store_short v[32:33], v17, off offset:192
	s_waitcnt lgkmcnt(0)
	v_add_f32_e32 v1, v16, v77
	v_mov_b32_e32 v244, v1
	v_mov_b32_e32 v16, v1
	s_nop 1
	v_permlane16_swap_b32_e32 v244, v16
	s_and_saveexec_b64 s[4:5], vcc
	s_cbranch_execz .LBB0_680
	s_waitcnt lgkmcnt(0)
	v_add_f32_e32 v1, v1, v16
	global_atomic_add_f32 v0, v1, s[0:1] offset:4
; __device__ __forceinline__ int crow(int r, int hi) { return (r & 3) + 8 * (r >> 2) + 4 * hi; }
; __device__ __forceinline__ unsigned cvtpk(float lo, float hi) { const f32x2_t v = {lo, hi}; return __builtin_bit_cast(unsigned, __builtin_convertvector(v, bf16x2_t)); }
; __device__ __forceinline__ void attn_body(const bf16_t* __restrict__ Qb, const bf16_t* __restrict__ KVb, int hcol, bf16_t* __restrict__ Ob, float* __restrict__ rsqa, int seq, char* lds) {
;     ...
;   for (int r = 0; r < 16; ++r) { int orow = crow(r, hi); float sq = 0.f;
; #pragma unroll
;     for (int d0 = 0; d0 < 4; ++d0) { const float v = o[d0][r] * rli[r]; sq += v * v; Ow[(long)orow * LDO + d0 * 32 + r32] = (bf16_t)(cvtpk(v, 0.f) & 0xffffu); }
;     sq += __shfl_xor(sq, 1); sq += __shfl_xor(sq, 2); sq += __shfl_xor(sq, 4); sq += __shfl_xor(sq, 8); sq += __shfl_xor(sq, 16);
;     if (r32 == 0) atomicAdd(rsqa + wid * QBLK + orow, sq); }
.LBB0_680:
	s_or_b64 exec, exec, s[4:5]
	v_rcp_f32_e32 v1, v78
	v_lshl_or_b32 v166, v76, 12, v172
	v_mul_f32_e32 v32, v50, v1
	v_mul_f32_e32 v2, v2, v1
	s_waitcnt lgkmcnt(0)
	v_mul_f32_e32 v16, v32, v32
	v_mul_f32_e32 v33, v34, v1
	v_fmac_f32_e32 v16, v2, v2
	v_fmac_f32_e32 v16, v33, v33
	v_mul_f32_e32 v18, v18, v1
	v_fmac_f32_e32 v16, v18, v18
	s_nop 1
	v_mov_b32_dpp v1, v16 quad_perm:[1,0,3,2] row_mask:0xf bank_mask:0xf
	v_cvt_pk_bf16_f32 v2, v2, s0
	v_cvt_pk_bf16_f32 v18, v18, s0
	s_waitcnt lgkmcnt(0)
	v_add_f32_e32 v1, v16, v1
	s_nop 1
	v_mov_b32_dpp v16, v1 quad_perm:[2,3,0,1] row_mask:0xf bank_mask:0xf
	s_waitcnt lgkmcnt(0)
	v_add_f32_e32 v1, v1, v16
	s_nop 1
	v_mov_b32_dpp v34, v1 row_half_mirror row_mask:0xf bank_mask:0xf
	v_lshl_add_u64 v[16:17], v[80:81], 0, v[166:167]
	global_store_short v[16:17], v2, off
	v_cvt_pk_bf16_f32 v2, v32, s0
	global_store_short v[16:17], v2, off offset:64
	s_waitcnt lgkmcnt(0)
	v_add_f32_e32 v1, v1, v34
	s_nop 1
	v_mov_b32_dpp v34, v1 row_mirror row_mask:0xf bank_mask:0xf
	v_cvt_pk_bf16_f32 v32, v33, s0
	global_store_short v[16:17], v32, off offset:128
	global_store_short v[16:17], v18, off offset:192
	s_waitcnt lgkmcnt(0)
	v_add_f32_e32 v1, v1, v34
	v_mov_b32_e32 v244, v1
	v_mov_b32_e32 v2, v1
	s_nop 1
	v_permlane16_swap_b32_e32 v244, v2
	s_and_saveexec_b64 s[4:5], vcc
	s_cbranch_execz .LBB0_682
	s_waitcnt lgkmcnt(0)
	v_add_f32_e32 v1, v1, v2
	global_atomic_add_f32 v0, v1, s[0:1] offset:8
.LBB0_682:
	s_or_b64 exec, exec, s[4:5]
	v_rcp_f32_e32 v1, v79
	v_lshl_or_b32 v166, v76, 12, v173
	s_waitcnt lgkmcnt(0)
	v_mul_f32_e32 v2, v3, v1
	v_mul_f32_e32 v3, v51, v1
	v_mul_f32_e32 v16, v3, v3
	v_mul_f32_e32 v18, v35, v1
	v_fmac_f32_e32 v16, v2, v2
	v_fmac_f32_e32 v16, v18, v18
	v_mul_f32_e32 v19, v19, v1
	v_fmac_f32_e32 v16, v19, v19
	s_nop 1
	v_mov_b32_dpp v1, v16 quad_perm:[1,0,3,2] row_mask:0xf bank_mask:0xf
	v_cvt_pk_bf16_f32 v2, v2, s0
	s_waitcnt lgkmcnt(0)
	v_add_f32_e32 v1, v16, v1
	s_nop 1
	v_mov_b32_dpp v16, v1 quad_perm:[2,3,0,1] row_mask:0xf bank_mask:0xf
	s_waitcnt lgkmcnt(0)
	v_add_f32_e32 v1, v1, v16
	s_nop 1
	v_mov_b32_dpp v32, v1 row_half_mirror row_mask:0xf bank_mask:0xf
	v_lshl_add_u64 v[16:17], v[80:81], 0, v[166:167]
	global_store_short v[16:17], v2, off
	v_cvt_pk_bf16_f32 v2, v3, s0
	global_store_short v[16:17], v2, off offset:64
	s_waitcnt lgkmcnt(0)
	v_add_f32_e32 v1, v1, v32
	s_nop 1
	v_mov_b32_dpp v32, v1 row_mirror row_mask:0xf bank_mask:0xf
	v_cvt_pk_bf16_f32 v3, v18, s0
	global_store_short v[16:17], v3, off offset:128
	v_cvt_pk_bf16_f32 v3, v19, s0
	global_store_short v[16:17], v3, off offset:192
	s_waitcnt lgkmcnt(0)
	v_add_f32_e32 v1, v1, v32
	v_mov_b32_e32 v244, v1
	v_mov_b32_e32 v2, v1
	s_nop 1
	v_permlane16_swap_b32_e32 v244, v2
	s_and_saveexec_b64 s[4:5], vcc
	s_cbranch_execz .LBB0_684
	s_waitcnt lgkmcnt(0)
	v_add_f32_e32 v1, v1, v2
	global_atomic_add_f32 v0, v1, s[0:1] offset:12
.LBB0_684:
	s_or_b64 exec, exec, s[4:5]
	v_rcp_f32_e32 v1, v72
	v_lshl_or_b32 v166, v76, 12, v174
	v_mul_f32_e32 v3, v52, v1
	s_waitcnt lgkmcnt(0)
	v_mul_f32_e32 v2, v4, v1
	v_mul_f32_e32 v16, v3, v3
	v_mul_f32_e32 v4, v36, v1
	v_fmac_f32_e32 v16, v2, v2
	v_fmac_f32_e32 v16, v4, v4
	v_mul_f32_e32 v18, v20, v1
	v_fmac_f32_e32 v16, v18, v18
	s_nop 1
	v_mov_b32_dpp v1, v16 quad_perm:[1,0,3,2] row_mask:0xf bank_mask:0xf
	v_cvt_pk_bf16_f32 v2, v2, s0
	s_waitcnt lgkmcnt(0)
	v_add_f32_e32 v1, v16, v1
	s_nop 1
	v_mov_b32_dpp v16, v1 quad_perm:[2,3,0,1] row_mask:0xf bank_mask:0xf
	s_waitcnt lgkmcnt(0)
	v_add_f32_e32 v1, v1, v16
	s_nop 1
	v_mov_b32_dpp v19, v1 row_half_mirror row_mask:0xf bank_mask:0xf
	v_lshl_add_u64 v[16:17], v[80:81], 0, v[166:167]
	global_store_short v[16:17], v2, off
	v_cvt_pk_bf16_f32 v2, v3, s0
	global_store_short v[16:17], v2, off offset:64
	s_waitcnt lgkmcnt(0)
	v_add_f32_e32 v1, v1, v19
	s_nop 1
	v_mov_b32_dpp v19, v1 row_mirror row_mask:0xf bank_mask:0xf
	v_cvt_pk_bf16_f32 v3, v4, s0
	global_store_short v[16:17], v3, off offset:128
	v_cvt_pk_bf16_f32 v3, v18, s0
	global_store_short v[16:17], v3, off offset:192
	s_waitcnt lgkmcnt(0)
	v_add_f32_e32 v1, v1, v19
	v_mov_b32_e32 v244, v1
	v_mov_b32_e32 v2, v1
	s_nop 1
	v_permlane16_swap_b32_e32 v244, v2
	s_and_saveexec_b64 s[4:5], vcc
	s_cbranch_execz .LBB0_686
	s_waitcnt lgkmcnt(0)
	v_add_f32_e32 v1, v1, v2
	global_atomic_add_f32 v0, v1, s[0:1] offset:32
.LBB0_686:
	s_or_b64 exec, exec, s[4:5]
	v_rcp_f32_e32 v1, v73
	v_lshl_or_b32 v166, v76, 12, v175
	v_mul_f32_e32 v3, v53, v1
	s_waitcnt lgkmcnt(0)
	v_mul_f32_e32 v2, v5, v1
	v_mul_f32_e32 v4, v3, v3
	v_mul_f32_e32 v16, v37, v1
	v_fmac_f32_e32 v4, v2, v2
	v_fmac_f32_e32 v4, v16, v16
	v_mul_f32_e32 v17, v21, v1
	v_fmac_f32_e32 v4, v17, v17
	s_nop 1
	v_mov_b32_dpp v1, v4 quad_perm:[1,0,3,2] row_mask:0xf bank_mask:0xf
	v_cvt_pk_bf16_f32 v2, v2, s0
	s_waitcnt lgkmcnt(0)
	v_add_f32_e32 v1, v4, v1
	s_nop 1
	v_mov_b32_dpp v4, v1 quad_perm:[2,3,0,1] row_mask:0xf bank_mask:0xf
	s_waitcnt lgkmcnt(0)
	v_add_f32_e32 v1, v1, v4
	s_nop 1
	v_mov_b32_dpp v18, v1 row_half_mirror row_mask:0xf bank_mask:0xf
	v_lshl_add_u64 v[4:5], v[80:81], 0, v[166:167]
	global_store_short v[4:5], v2, off
	v_cvt_pk_bf16_f32 v2, v3, s0
	global_store_short v[4:5], v2, off offset:64
	s_waitcnt lgkmcnt(0)
	v_add_f32_e32 v1, v1, v18
	s_nop 1
	v_mov_b32_dpp v18, v1 row_mirror row_mask:0xf bank_mask:0xf
	v_cvt_pk_bf16_f32 v3, v16, s0
	global_store_short v[4:5], v3, off offset:128
	v_cvt_pk_bf16_f32 v3, v17, s0
	global_store_short v[4:5], v3, off offset:192
	s_waitcnt lgkmcnt(0)
	v_add_f32_e32 v1, v1, v18
	v_mov_b32_e32 v244, v1
	v_mov_b32_e32 v2, v1
	s_nop 1
	v_permlane16_swap_b32_e32 v244, v2
	s_and_saveexec_b64 s[4:5], vcc
	s_cbranch_execz .LBB0_688
	s_waitcnt lgkmcnt(0)
	v_add_f32_e32 v1, v1, v2
	global_atomic_add_f32 v0, v1, s[0:1] offset:36
; __device__ __forceinline__ int crow(int r, int hi) { return (r & 3) + 8 * (r >> 2) + 4 * hi; }
; __device__ __forceinline__ unsigned cvtpk(float lo, float hi) { const f32x2_t v = {lo, hi}; return __builtin_bit_cast(unsigned, __builtin_convertvector(v, bf16x2_t)); }
; __device__ __forceinline__ void attn_body(const bf16_t* __restrict__ Qb, const bf16_t* __restrict__ KVb, int hcol, bf16_t* __restrict__ Ob, float* __restrict__ rsqa, int seq, char* lds) {
;     ...
;   for (int r = 0; r < 16; ++r) { int orow = crow(r, hi); float sq = 0.f;
; #pragma unroll
;     for (int d0 = 0; d0 < 4; ++d0) { const float v = o[d0][r] * rli[r]; sq += v * v; Ow[(long)orow * LDO + d0 * 32 + r32] = (bf16_t)(cvtpk(v, 0.f) & 0xffffu); }
;     sq += __shfl_xor(sq, 1); sq += __shfl_xor(sq, 2); sq += __shfl_xor(sq, 4); sq += __shfl_xor(sq, 8); sq += __shfl_xor(sq, 16);
;     if (r32 == 0) atomicAdd(rsqa + wid * QBLK + orow, sq); }
.LBB0_688:
	s_or_b64 exec, exec, s[4:5]
	v_rcp_f32_e32 v1, v74
	v_lshl_or_b32 v166, v76, 12, v176
	v_mul_f32_e32 v3, v54, v1
	s_waitcnt lgkmcnt(0)
	v_mul_f32_e32 v2, v6, v1
	v_mul_f32_e32 v4, v3, v3
	v_mul_f32_e32 v6, v38, v1
	v_fmac_f32_e32 v4, v2, v2
	v_fmac_f32_e32 v4, v6, v6
	v_mul_f32_e32 v16, v22, v1
	v_fmac_f32_e32 v4, v16, v16
	s_nop 1
	v_mov_b32_dpp v1, v4 quad_perm:[1,0,3,2] row_mask:0xf bank_mask:0xf
	v_cvt_pk_bf16_f32 v2, v2, s0
	s_waitcnt lgkmcnt(0)
	v_add_f32_e32 v1, v4, v1
	s_nop 1
	v_mov_b32_dpp v4, v1 quad_perm:[2,3,0,1] row_mask:0xf bank_mask:0xf
	s_waitcnt lgkmcnt(0)
	v_add_f32_e32 v1, v1, v4
	s_nop 1
	v_mov_b32_dpp v17, v1 row_half_mirror row_mask:0xf bank_mask:0xf
	v_lshl_add_u64 v[4:5], v[80:81], 0, v[166:167]
	global_store_short v[4:5], v2, off
	v_cvt_pk_bf16_f32 v2, v3, s0
	global_store_short v[4:5], v2, off offset:64
	s_waitcnt lgkmcnt(0)
	v_add_f32_e32 v1, v1, v17
	s_nop 1
	v_mov_b32_dpp v17, v1 row_mirror row_mask:0xf bank_mask:0xf
	v_cvt_pk_bf16_f32 v3, v6, s0
	global_store_short v[4:5], v3, off offset:128
	v_cvt_pk_bf16_f32 v3, v16, s0
	global_store_short v[4:5], v3, off offset:192
	s_waitcnt lgkmcnt(0)
	v_add_f32_e32 v1, v1, v17
	v_mov_b32_e32 v244, v1
	v_mov_b32_e32 v2, v1
	s_nop 1
	v_permlane16_swap_b32_e32 v244, v2
	s_and_saveexec_b64 s[4:5], vcc
	s_cbranch_execz .LBB0_690
	s_waitcnt lgkmcnt(0)
	v_add_f32_e32 v1, v1, v2
	global_atomic_add_f32 v0, v1, s[0:1] offset:40
.LBB0_690:
	s_or_b64 exec, exec, s[4:5]
	v_rcp_f32_e32 v1, v75
	v_lshl_or_b32 v166, v76, 12, v177
	v_mul_f32_e32 v3, v55, v1
	s_waitcnt lgkmcnt(0)
	v_mul_f32_e32 v2, v7, v1
	v_mul_f32_e32 v4, v3, v3
	v_mul_f32_e32 v6, v39, v1
	v_fmac_f32_e32 v4, v2, v2
	v_fmac_f32_e32 v4, v6, v6
	v_mul_f32_e32 v7, v23, v1
	v_fmac_f32_e32 v4, v7, v7
	s_nop 1
	v_mov_b32_dpp v1, v4 quad_perm:[1,0,3,2] row_mask:0xf bank_mask:0xf
	v_cvt_pk_bf16_f32 v2, v2, s0
	s_waitcnt lgkmcnt(0)
	v_add_f32_e32 v1, v4, v1
	s_nop 1
	v_mov_b32_dpp v4, v1 quad_perm:[2,3,0,1] row_mask:0xf bank_mask:0xf
	s_waitcnt lgkmcnt(0)
	v_add_f32_e32 v1, v1, v4
	s_nop 1
	v_mov_b32_dpp v16, v1 row_half_mirror row_mask:0xf bank_mask:0xf
	v_lshl_add_u64 v[4:5], v[80:81], 0, v[166:167]
	global_store_short v[4:5], v2, off
	v_cvt_pk_bf16_f32 v2, v3, s0
	global_store_short v[4:5], v2, off offset:64
	s_waitcnt lgkmcnt(0)
	v_add_f32_e32 v1, v1, v16
	s_nop 1
	v_mov_b32_dpp v16, v1 row_mirror row_mask:0xf bank_mask:0xf
	v_cvt_pk_bf16_f32 v3, v6, s0
	global_store_short v[4:5], v3, off offset:128
	v_cvt_pk_bf16_f32 v3, v7, s0
	global_store_short v[4:5], v3, off offset:192
	s_waitcnt lgkmcnt(0)
	v_add_f32_e32 v1, v1, v16
	v_mov_b32_e32 v244, v1
	v_mov_b32_e32 v2, v1
	s_nop 1
	v_permlane16_swap_b32_e32 v244, v2
	s_and_saveexec_b64 s[4:5], vcc
	s_cbranch_execz .LBB0_692
	s_waitcnt lgkmcnt(0)
	v_add_f32_e32 v1, v1, v2
	global_atomic_add_f32 v0, v1, s[0:1] offset:44
.LBB0_692:
	s_or_b64 exec, exec, s[4:5]
	v_rcp_f32_e32 v1, v68
	v_lshl_or_b32 v166, v76, 12, v178
	v_mul_f32_e32 v3, v56, v1
	s_waitcnt lgkmcnt(0)
	v_mul_f32_e32 v2, v8, v1
	v_mul_f32_e32 v4, v3, v3
	v_mul_f32_e32 v6, v40, v1
	v_fmac_f32_e32 v4, v2, v2
	v_fmac_f32_e32 v4, v6, v6
	v_mul_f32_e32 v7, v24, v1
	v_fmac_f32_e32 v4, v7, v7
	s_nop 1
	v_mov_b32_dpp v1, v4 quad_perm:[1,0,3,2] row_mask:0xf bank_mask:0xf
	v_cvt_pk_bf16_f32 v2, v2, s0
	s_waitcnt lgkmcnt(0)
	v_add_f32_e32 v1, v4, v1
	s_nop 1
	v_mov_b32_dpp v4, v1 quad_perm:[2,3,0,1] row_mask:0xf bank_mask:0xf
	s_waitcnt lgkmcnt(0)
	v_add_f32_e32 v1, v1, v4
	s_nop 1
	v_mov_b32_dpp v8, v1 row_half_mirror row_mask:0xf bank_mask:0xf
	v_lshl_add_u64 v[4:5], v[80:81], 0, v[166:167]
	global_store_short v[4:5], v2, off
	v_cvt_pk_bf16_f32 v2, v3, s0
	global_store_short v[4:5], v2, off offset:64
	s_waitcnt lgkmcnt(0)
	v_add_f32_e32 v1, v1, v8
	s_nop 1
	v_mov_b32_dpp v8, v1 row_mirror row_mask:0xf bank_mask:0xf
	v_cvt_pk_bf16_f32 v3, v6, s0
	global_store_short v[4:5], v3, off offset:128
	v_cvt_pk_bf16_f32 v3, v7, s0
	global_store_short v[4:5], v3, off offset:192
	s_waitcnt lgkmcnt(0)
	v_add_f32_e32 v1, v1, v8
	v_mov_b32_e32 v244, v1
	v_mov_b32_e32 v2, v1
	s_nop 1
	v_permlane16_swap_b32_e32 v244, v2
	s_and_saveexec_b64 s[4:5], vcc
	s_cbranch_execz .LBB0_694
	s_waitcnt lgkmcnt(0)
	v_add_f32_e32 v1, v1, v2
	global_atomic_add_f32 v0, v1, s[0:1] offset:64
.LBB0_694:
	s_or_b64 exec, exec, s[4:5]
	v_rcp_f32_e32 v1, v69
	v_lshl_or_b32 v166, v76, 12, v179
	v_mul_f32_e32 v3, v57, v1
	s_waitcnt lgkmcnt(0)
	v_mul_f32_e32 v2, v9, v1
	v_mul_f32_e32 v4, v3, v3
	v_mul_f32_e32 v6, v41, v1
	v_fmac_f32_e32 v4, v2, v2
	v_fmac_f32_e32 v4, v6, v6
	v_mul_f32_e32 v7, v25, v1
	v_fmac_f32_e32 v4, v7, v7
	s_nop 1
	v_mov_b32_dpp v1, v4 quad_perm:[1,0,3,2] row_mask:0xf bank_mask:0xf
	v_cvt_pk_bf16_f32 v2, v2, s0
	s_waitcnt lgkmcnt(0)
	v_add_f32_e32 v1, v4, v1
	s_nop 1
	v_mov_b32_dpp v4, v1 quad_perm:[2,3,0,1] row_mask:0xf bank_mask:0xf
	s_waitcnt lgkmcnt(0)
	v_add_f32_e32 v1, v1, v4
	s_nop 1
	v_mov_b32_dpp v8, v1 row_half_mirror row_mask:0xf bank_mask:0xf
	v_lshl_add_u64 v[4:5], v[80:81], 0, v[166:167]
	global_store_short v[4:5], v2, off
	v_cvt_pk_bf16_f32 v2, v3, s0
	global_store_short v[4:5], v2, off offset:64
	s_waitcnt lgkmcnt(0)
	v_add_f32_e32 v1, v1, v8
	s_nop 1
	v_mov_b32_dpp v8, v1 row_mirror row_mask:0xf bank_mask:0xf
	v_cvt_pk_bf16_f32 v3, v6, s0
	global_store_short v[4:5], v3, off offset:128
	v_cvt_pk_bf16_f32 v3, v7, s0
	global_store_short v[4:5], v3, off offset:192
	s_waitcnt lgkmcnt(0)
	v_add_f32_e32 v1, v1, v8
	v_mov_b32_e32 v244, v1
	v_mov_b32_e32 v2, v1
	s_nop 1
	v_permlane16_swap_b32_e32 v244, v2
	s_and_saveexec_b64 s[4:5], vcc
	s_cbranch_execz .LBB0_696
	s_waitcnt lgkmcnt(0)
	v_add_f32_e32 v1, v1, v2
	global_atomic_add_f32 v0, v1, s[0:1] offset:68
; __device__ __forceinline__ int crow(int r, int hi) { return (r & 3) + 8 * (r >> 2) + 4 * hi; }
; __device__ __forceinline__ unsigned cvtpk(float lo, float hi) { const f32x2_t v = {lo, hi}; return __builtin_bit_cast(unsigned, __builtin_convertvector(v, bf16x2_t)); }
; __device__ __forceinline__ void attn_body(const bf16_t* __restrict__ Qb, const bf16_t* __restrict__ KVb, int hcol, bf16_t* __restrict__ Ob, float* __restrict__ rsqa, int seq, char* lds) {
;     ...
;   for (int r = 0; r < 16; ++r) { int orow = crow(r, hi); float sq = 0.f;
; #pragma unroll
;     for (int d0 = 0; d0 < 4; ++d0) { const float v = o[d0][r] * rli[r]; sq += v * v; Ow[(long)orow * LDO + d0 * 32 + r32] = (bf16_t)(cvtpk(v, 0.f) & 0xffffu); }
;     sq += __shfl_xor(sq, 1); sq += __shfl_xor(sq, 2); sq += __shfl_xor(sq, 4); sq += __shfl_xor(sq, 8); sq += __shfl_xor(sq, 16);
;     if (r32 == 0) atomicAdd(rsqa + wid * QBLK + orow, sq); }
.LBB0_696:
	s_or_b64 exec, exec, s[4:5]
	v_rcp_f32_e32 v1, v70
	v_lshl_or_b32 v166, v76, 12, v180
	v_mul_f32_e32 v3, v58, v1
	s_waitcnt lgkmcnt(0)
	v_mul_f32_e32 v2, v10, v1
	v_mul_f32_e32 v4, v3, v3
	v_mul_f32_e32 v6, v42, v1
	v_fmac_f32_e32 v4, v2, v2
	v_fmac_f32_e32 v4, v6, v6
	v_mul_f32_e32 v7, v26, v1
	v_fmac_f32_e32 v4, v7, v7
	s_nop 1
	v_mov_b32_dpp v1, v4 quad_perm:[1,0,3,2] row_mask:0xf bank_mask:0xf
	v_cvt_pk_bf16_f32 v2, v2, s0
	s_waitcnt lgkmcnt(0)
	v_add_f32_e32 v1, v4, v1
	s_nop 1
	v_mov_b32_dpp v4, v1 quad_perm:[2,3,0,1] row_mask:0xf bank_mask:0xf
	s_waitcnt lgkmcnt(0)
	v_add_f32_e32 v1, v1, v4
	s_nop 1
	v_mov_b32_dpp v8, v1 row_half_mirror row_mask:0xf bank_mask:0xf
	v_lshl_add_u64 v[4:5], v[80:81], 0, v[166:167]
	global_store_short v[4:5], v2, off
	v_cvt_pk_bf16_f32 v2, v3, s0
	global_store_short v[4:5], v2, off offset:64
	s_waitcnt lgkmcnt(0)
	v_add_f32_e32 v1, v1, v8
	s_nop 1
	v_mov_b32_dpp v8, v1 row_mirror row_mask:0xf bank_mask:0xf
	v_cvt_pk_bf16_f32 v3, v6, s0
	global_store_short v[4:5], v3, off offset:128
	v_cvt_pk_bf16_f32 v3, v7, s0
	global_store_short v[4:5], v3, off offset:192
	s_waitcnt lgkmcnt(0)
	v_add_f32_e32 v1, v1, v8
	v_mov_b32_e32 v244, v1
	v_mov_b32_e32 v2, v1
	s_nop 1
	v_permlane16_swap_b32_e32 v244, v2
	s_and_saveexec_b64 s[4:5], vcc
	s_cbranch_execz .LBB0_698
	s_waitcnt lgkmcnt(0)
	v_add_f32_e32 v1, v1, v2
	global_atomic_add_f32 v0, v1, s[0:1] offset:72
.LBB0_698:
	s_or_b64 exec, exec, s[4:5]
	v_rcp_f32_e32 v1, v71
	v_lshl_or_b32 v166, v76, 12, v181
	v_mul_f32_e32 v3, v59, v1
	s_waitcnt lgkmcnt(0)
	v_mul_f32_e32 v2, v11, v1
	v_mul_f32_e32 v4, v3, v3
	v_mul_f32_e32 v6, v43, v1
	v_fmac_f32_e32 v4, v2, v2
	v_fmac_f32_e32 v4, v6, v6
	v_mul_f32_e32 v7, v27, v1
	v_fmac_f32_e32 v4, v7, v7
	s_nop 1
	v_mov_b32_dpp v1, v4 quad_perm:[1,0,3,2] row_mask:0xf bank_mask:0xf
	v_cvt_pk_bf16_f32 v2, v2, s0
	s_waitcnt lgkmcnt(0)
	v_add_f32_e32 v1, v4, v1
	s_nop 1
	v_mov_b32_dpp v4, v1 quad_perm:[2,3,0,1] row_mask:0xf bank_mask:0xf
	s_waitcnt lgkmcnt(0)
	v_add_f32_e32 v1, v1, v4
	s_nop 1
	v_mov_b32_dpp v8, v1 row_half_mirror row_mask:0xf bank_mask:0xf
	v_lshl_add_u64 v[4:5], v[80:81], 0, v[166:167]
	global_store_short v[4:5], v2, off
	v_cvt_pk_bf16_f32 v2, v3, s0
	global_store_short v[4:5], v2, off offset:64
	s_waitcnt lgkmcnt(0)
	v_add_f32_e32 v1, v1, v8
	s_nop 1
	v_mov_b32_dpp v8, v1 row_mirror row_mask:0xf bank_mask:0xf
	v_cvt_pk_bf16_f32 v3, v6, s0
	global_store_short v[4:5], v3, off offset:128
	v_cvt_pk_bf16_f32 v3, v7, s0
	global_store_short v[4:5], v3, off offset:192
	s_waitcnt lgkmcnt(0)
	v_add_f32_e32 v1, v1, v8
	v_mov_b32_e32 v244, v1
	v_mov_b32_e32 v2, v1
	s_nop 1
	v_permlane16_swap_b32_e32 v244, v2
	s_and_saveexec_b64 s[4:5], vcc
	s_cbranch_execz .LBB0_700
	s_waitcnt lgkmcnt(0)
	v_add_f32_e32 v1, v1, v2
	global_atomic_add_f32 v0, v1, s[0:1] offset:76
.LBB0_700:
	s_or_b64 exec, exec, s[4:5]
	v_rcp_f32_e32 v1, v64
	v_lshl_or_b32 v166, v76, 12, v182
	v_mul_f32_e32 v3, v60, v1
	s_waitcnt lgkmcnt(0)
	v_mul_f32_e32 v2, v12, v1
	v_mul_f32_e32 v4, v3, v3
	v_mul_f32_e32 v6, v44, v1
	v_fmac_f32_e32 v4, v2, v2
	v_fmac_f32_e32 v4, v6, v6
	v_mul_f32_e32 v7, v28, v1
	v_fmac_f32_e32 v4, v7, v7
	s_nop 1
	v_mov_b32_dpp v1, v4 quad_perm:[1,0,3,2] row_mask:0xf bank_mask:0xf
	v_cvt_pk_bf16_f32 v2, v2, s0
	s_waitcnt lgkmcnt(0)
	v_add_f32_e32 v1, v4, v1
	s_nop 1
	v_mov_b32_dpp v4, v1 quad_perm:[2,3,0,1] row_mask:0xf bank_mask:0xf
	s_waitcnt lgkmcnt(0)
	v_add_f32_e32 v1, v1, v4
	s_nop 1
	v_mov_b32_dpp v8, v1 row_half_mirror row_mask:0xf bank_mask:0xf
	v_lshl_add_u64 v[4:5], v[80:81], 0, v[166:167]
	global_store_short v[4:5], v2, off
	v_cvt_pk_bf16_f32 v2, v3, s0
	global_store_short v[4:5], v2, off offset:64
	s_waitcnt lgkmcnt(0)
	v_add_f32_e32 v1, v1, v8
	s_nop 1
	v_mov_b32_dpp v8, v1 row_mirror row_mask:0xf bank_mask:0xf
	v_cvt_pk_bf16_f32 v3, v6, s0
	global_store_short v[4:5], v3, off offset:128
	v_cvt_pk_bf16_f32 v3, v7, s0
	global_store_short v[4:5], v3, off offset:192
	s_waitcnt lgkmcnt(0)
	v_add_f32_e32 v1, v1, v8
	v_mov_b32_e32 v244, v1
	v_mov_b32_e32 v2, v1
	s_nop 1
	v_permlane16_swap_b32_e32 v244, v2
	s_and_saveexec_b64 s[4:5], vcc
	s_cbranch_execz .LBB0_702
	s_waitcnt lgkmcnt(0)
	v_add_f32_e32 v1, v1, v2
	global_atomic_add_f32 v0, v1, s[0:1] offset:96
; __device__ __forceinline__ int crow(int r, int hi) { return (r & 3) + 8 * (r >> 2) + 4 * hi; }
; __device__ __forceinline__ unsigned cvtpk(float lo, float hi) { const f32x2_t v = {lo, hi}; return __builtin_bit_cast(unsigned, __builtin_convertvector(v, bf16x2_t)); }
; __device__ __forceinline__ void attn_body(const bf16_t* __restrict__ Qb, const bf16_t* __restrict__ KVb, int hcol, bf16_t* __restrict__ Ob, float* __restrict__ rsqa, int seq, char* lds) {
;     ...
;   for (int r = 0; r < 16; ++r) { int orow = crow(r, hi); float sq = 0.f;
; #pragma unroll
;     for (int d0 = 0; d0 < 4; ++d0) { const float v = o[d0][r] * rli[r]; sq += v * v; Ow[(long)orow * LDO + d0 * 32 + r32] = (bf16_t)(cvtpk(v, 0.f) & 0xffffu); }
;     sq += __shfl_xor(sq, 1); sq += __shfl_xor(sq, 2); sq += __shfl_xor(sq, 4); sq += __shfl_xor(sq, 8); sq += __shfl_xor(sq, 16);
;     if (r32 == 0) atomicAdd(rsqa + wid * QBLK + orow, sq); }
.LBB0_702:
	s_or_b64 exec, exec, s[4:5]
	v_rcp_f32_e32 v1, v65
	v_lshl_or_b32 v166, v76, 12, v183
	v_mul_f32_e32 v3, v61, v1
	s_waitcnt lgkmcnt(0)
	v_mul_f32_e32 v2, v13, v1
	v_mul_f32_e32 v4, v3, v3
	v_mul_f32_e32 v6, v45, v1
	v_fmac_f32_e32 v4, v2, v2
	v_fmac_f32_e32 v4, v6, v6
	v_mul_f32_e32 v7, v29, v1
	v_fmac_f32_e32 v4, v7, v7
	s_nop 1
	v_mov_b32_dpp v1, v4 quad_perm:[1,0,3,2] row_mask:0xf bank_mask:0xf
	v_cvt_pk_bf16_f32 v2, v2, s0
	s_waitcnt lgkmcnt(0)
	v_add_f32_e32 v1, v4, v1
	s_nop 1
	v_mov_b32_dpp v4, v1 quad_perm:[2,3,0,1] row_mask:0xf bank_mask:0xf
	s_waitcnt lgkmcnt(0)
	v_add_f32_e32 v1, v1, v4
	s_nop 1
	v_mov_b32_dpp v8, v1 row_half_mirror row_mask:0xf bank_mask:0xf
	v_lshl_add_u64 v[4:5], v[80:81], 0, v[166:167]
	global_store_short v[4:5], v2, off
	v_cvt_pk_bf16_f32 v2, v3, s0
	global_store_short v[4:5], v2, off offset:64
	s_waitcnt lgkmcnt(0)
	v_add_f32_e32 v1, v1, v8
	s_nop 1
	v_mov_b32_dpp v8, v1 row_mirror row_mask:0xf bank_mask:0xf
	v_cvt_pk_bf16_f32 v3, v6, s0
	global_store_short v[4:5], v3, off offset:128
	v_cvt_pk_bf16_f32 v3, v7, s0
	global_store_short v[4:5], v3, off offset:192
	s_waitcnt lgkmcnt(0)
	v_add_f32_e32 v1, v1, v8
	v_mov_b32_e32 v244, v1
	v_mov_b32_e32 v2, v1
	s_nop 1
	v_permlane16_swap_b32_e32 v244, v2
	s_and_saveexec_b64 s[4:5], vcc
	s_cbranch_execz .LBB0_704
	s_waitcnt lgkmcnt(0)
	v_add_f32_e32 v1, v1, v2
	global_atomic_add_f32 v0, v1, s[0:1] offset:100
.LBB0_704:
	s_or_b64 exec, exec, s[4:5]
	v_rcp_f32_e32 v1, v66
	v_lshl_or_b32 v166, v76, 12, v184
	v_mul_f32_e32 v3, v62, v1
	s_waitcnt lgkmcnt(0)
	v_mul_f32_e32 v2, v14, v1
	v_mul_f32_e32 v4, v3, v3
	v_mul_f32_e32 v6, v46, v1
	v_fmac_f32_e32 v4, v2, v2
	v_fmac_f32_e32 v4, v6, v6
	v_mul_f32_e32 v7, v30, v1
	v_fmac_f32_e32 v4, v7, v7
	s_nop 1
	v_mov_b32_dpp v1, v4 quad_perm:[1,0,3,2] row_mask:0xf bank_mask:0xf
	v_cvt_pk_bf16_f32 v2, v2, s0
	s_waitcnt lgkmcnt(0)
	v_add_f32_e32 v1, v4, v1
	s_nop 1
	v_mov_b32_dpp v4, v1 quad_perm:[2,3,0,1] row_mask:0xf bank_mask:0xf
	s_waitcnt lgkmcnt(0)
	v_add_f32_e32 v1, v1, v4
	s_nop 1
	v_mov_b32_dpp v8, v1 row_half_mirror row_mask:0xf bank_mask:0xf
	v_lshl_add_u64 v[4:5], v[80:81], 0, v[166:167]
	global_store_short v[4:5], v2, off
	v_cvt_pk_bf16_f32 v2, v3, s0
	global_store_short v[4:5], v2, off offset:64
	s_waitcnt lgkmcnt(0)
	v_add_f32_e32 v1, v1, v8
	s_nop 1
	v_mov_b32_dpp v8, v1 row_mirror row_mask:0xf bank_mask:0xf
	v_cvt_pk_bf16_f32 v3, v6, s0
	global_store_short v[4:5], v3, off offset:128
	v_cvt_pk_bf16_f32 v3, v7, s0
	global_store_short v[4:5], v3, off offset:192
	s_waitcnt lgkmcnt(0)
	v_add_f32_e32 v1, v1, v8
	v_mov_b32_e32 v244, v1
	v_mov_b32_e32 v2, v1
	s_nop 1
	v_permlane16_swap_b32_e32 v244, v2
	s_and_saveexec_b64 s[4:5], vcc
	s_cbranch_execz .LBB0_706
	s_waitcnt lgkmcnt(0)
	v_add_f32_e32 v1, v1, v2
	global_atomic_add_f32 v0, v1, s[0:1] offset:104
.LBB0_706:
	s_or_b64 exec, exec, s[4:5]
	v_rcp_f32_e32 v1, v67
	v_lshl_or_b32 v166, v76, 12, v185
	v_mul_f32_e32 v3, v63, v1
	s_waitcnt lgkmcnt(0)
	v_mul_f32_e32 v2, v15, v1
	v_mul_f32_e32 v4, v3, v3
	v_mul_f32_e32 v6, v47, v1
	v_fmac_f32_e32 v4, v2, v2
	v_fmac_f32_e32 v4, v6, v6
	v_mul_f32_e32 v7, v31, v1
	v_fmac_f32_e32 v4, v7, v7
	s_nop 1
	v_mov_b32_dpp v1, v4 quad_perm:[1,0,3,2] row_mask:0xf bank_mask:0xf
	v_cvt_pk_bf16_f32 v2, v2, s0
	s_waitcnt lgkmcnt(0)
	v_add_f32_e32 v1, v4, v1
	s_nop 1
	v_mov_b32_dpp v4, v1 quad_perm:[2,3,0,1] row_mask:0xf bank_mask:0xf
	s_waitcnt lgkmcnt(0)
	v_add_f32_e32 v1, v1, v4
	s_nop 1
	v_mov_b32_dpp v8, v1 row_half_mirror row_mask:0xf bank_mask:0xf
	v_lshl_add_u64 v[4:5], v[80:81], 0, v[166:167]
	global_store_short v[4:5], v2, off
	v_cvt_pk_bf16_f32 v2, v3, s0
	global_store_short v[4:5], v2, off offset:64
	s_waitcnt lgkmcnt(0)
	v_add_f32_e32 v1, v1, v8
	s_nop 1
	v_mov_b32_dpp v8, v1 row_mirror row_mask:0xf bank_mask:0xf
	v_cvt_pk_bf16_f32 v3, v6, s0
	global_store_short v[4:5], v3, off offset:128
	v_cvt_pk_bf16_f32 v3, v7, s0
	global_store_short v[4:5], v3, off offset:192
	s_waitcnt lgkmcnt(0)
	v_add_f32_e32 v1, v1, v8
	v_mov_b32_e32 v244, v1
	v_mov_b32_e32 v2, v1
	s_nop 1
	v_permlane16_swap_b32_e32 v244, v2
	s_and_saveexec_b64 s[4:5], vcc
	s_cbranch_execz .LBB0_651
	s_waitcnt lgkmcnt(0)
	v_add_f32_e32 v1, v1, v2
	global_atomic_add_f32 v0, v1, s[0:1] offset:108
	s_branch .LBB0_651
